# MoBA unit prologue: issue q and first K/V loads before waiting for the k-mean table load (was serialized)
# speedup vs baseline: 1.0034x; 1.0034x over previous
; #define LAS __attribute__((address_space(3)))
; __device__ __forceinline__ int otid() { int t = threadIdx.x; asm volatile("" : "+v"(t)); return t; }
; #define MOBA_LOAD(t128) do { _Pragma("unroll") for (int ii = 0; ii < 2; ++ii) { const int cid = tid + 512 * ii; \
;         kreg[ii] = *(const u32x4*)(Kc + (size_t)((t128) * 128) * 64 + cid * 8); \
;         vreg[ii] = *(const u32x4*)(Vc + (size_t)((t128) * 128) * 64 + cid * 8); } } while (0)
; __device__ __forceinline__ void moba_unit(const Args& a, int l, LAS unsigned char* lds, int b, int h, int qb) {
;     const int tid = otid(), lane = tid & 63, w = __builtin_amdgcn_readfirstlane(tid >> 6), fr = lane & 15, fq = lane >> 4;
;     bf16_t* proj = (bf16_t*)(a.ws + WS_PROJ);
;     LAS float* kml = (LAS float*)(lds + 77824);
;     kml[tid] = ((const float*)(a.ws + WS_KMEAN))[(size_t)(b * 8 + h) * 512 + tid];
;     const size_t rowbase = (size_t)b * SEQ;
;     const bf16_t* Kc = (const bf16_t*)(a.ws + WS_KC) + (size_t)(b * 8 + h) * SEQ * 64; const bf16_t* Vc = (const bf16_t*)(a.ws + WS_VC) + (size_t)(b * 8 + h) * SEQ * 64;
;     const int qrow[2] = {qb * 256 + w * 16, qb * 256 + (15 - w) * 16};
;     bf16x8 qf[2][2];
; #pragma unroll
;     for (int qt = 0; qt < 2; ++qt)
; #pragma unroll
;         for (int ks = 0; ks < 2; ++ks) qf[qt][ks] = *(const bf16x8*)(proj + (rowbase + qrow[qt] + fr) * NCOL + CQA + h * 64 + ks * 32 + fq * 8);
;     const int NT2 = (qb + 1) * 2;
;     u32x4 kreg[2], vreg[2];
;     ...
;     MOBA_LOAD(MOBA_T128(0));
;     __syncthreads();
;     unsigned selmask[2];
.LBB0_548:
	v_mov_b32_e32 v78, v178
	s_ashr_i32 s15, s14, 31
	v_readfirstlane_b32 s4, v78
	s_ashr_i32 s8, s14, 3
	s_ashr_i32 s5, s4, 6
	s_lshl_b64 s[10:11], s[14:15], 11
	v_readlane_b32 s6, v245, 42
	s_add_u32 s10, s6, s10
	v_readlane_b32 s6, v245, 43
	v_ashrrev_i32_e32 v79, 31, v78
	s_addc_u32 s11, s6, s11
	v_lshl_add_u64 v[0:1], v[78:79], 2, s[10:11]
	global_load_dword v240, v[0:1], off
	s_lshl_b32 s16, s5, 4
	s_sub_i32 s5, 15, s5
	s_lshl_b32 s6, s19, 8
	s_lshl_b32 s17, s5, 4
	s_add_i32 s10, s16, s6
	s_add_i32 s36, s17, s6
	s_lshl_b32 s6, s14, 6
	s_ashr_i32 s9, s8, 31
	s_and_b32 s6, s6, 0x1c0
	v_lshl_add_u32 v241, v78, 2, 0
	s_lshl_b64 s[8:9], s[8:9], 11
	s_lshl_b32 s6, s6, 1
	v_and_b32_e32 v200, 15, v78
	v_add_u32_e32 v241, 0x13000, v241
	s_add_u32 s44, s84, s6
	v_bfe_u32 v115, v78, 4, 2
	s_addc_u32 s45, s85, 0
	s_ashr_i32 s11, s10, 31
	s_ashr_i32 s37, s36, 31
	v_lshlrev_b32_e32 v144, 4, v115
	v_lshl_add_u64 v[2:3], s[44:45], 0, v[144:145]
	v_or_b32_e32 v0, s8, v200
	v_mov_b32_e32 v1, s9
	v_lshl_add_u64 v[4:5], v[0:1], 0, s[10:11]
	v_lshl_add_u64 v[0:1], v[0:1], 0, s[36:37]
	s_lshl_b64 s[8:9], s[14:15], 18
	v_lshlrev_b64 v[142:143], 13, v[4:5]
	v_lshlrev_b64 v[140:141], 13, v[0:1]
	s_add_u32 s43, s33, s8
	v_lshl_add_u64 v[4:5], v[2:3], 0, v[142:143]
	v_lshl_add_u64 v[0:1], v[2:3], 0, v[140:141]
	s_addc_u32 s50, s20, s9
	global_load_dwordx4 v[20:23], v[4:5], off
	global_load_dwordx4 v[24:27], v[4:5], off offset:64
	global_load_dwordx4 v[28:31], v[0:1], off
	global_load_dwordx4 v[32:35], v[0:1], off offset:64
	s_add_u32 s51, s21, s8
	v_lshlrev_b32_e32 v0, 3, v78
	s_addc_u32 s52, s22, s9
	s_lshl_b32 s10, s19, 15
	v_ashrrev_i32_e32 v1, 31, v0
	s_add_u32 s8, s43, s10
	v_lshlrev_b64 v[156:157], 1, v[0:1]
	v_add_u32_e32 v0, 0x1000, v0
	s_addc_u32 s9, s50, 0
	v_ashrrev_i32_e32 v1, 31, v0
	s_add_u32 s10, s51, s10
	v_lshlrev_b64 v[158:159], 1, v[0:1]
	s_addc_u32 s11, s52, 0
	v_lshl_add_u64 v[2:3], s[8:9], 0, v[156:157]
	v_lshl_add_u64 v[0:1], s[8:9], 0, v[158:159]
	global_load_dwordx4 v[36:39], v[2:3], off
	global_load_dwordx4 v[44:47], v[0:1], off
	v_lshl_add_u64 v[2:3], s[10:11], 0, v[156:157]
	v_lshl_add_u64 v[0:1], s[10:11], 0, v[158:159]
	global_load_dwordx4 v[40:43], v[2:3], off
	global_load_dwordx4 v[48:51], v[0:1], off
	s_mov_b64 s[14:15], -1
	s_cmp_lt_u32 s19, 4
	s_waitcnt vmcnt(8)
	ds_write_b32 v241, v240
	s_waitcnt lgkmcnt(0)
	s_barrier
	s_cbranch_scc1 .LBB0_560
	v_lshl_add_u32 v0, v115, 5, 0
	v_add_u32_e32 v79, 0x13000, v0
	ds_read_b128 v[8:11], v79
	ds_read_b128 v[12:15], v79 offset:16
	ds_read_b128 v[0:3], v79 offset:256
	ds_read2_b64 v[74:77], v79 offset0:17 offset1:18
	ds_read_b128 v[58:61], v79 offset:272
	s_waitcnt vmcnt(7)
	v_lshlrev_b32_e32 v114, 16, v20
	s_waitcnt lgkmcnt(4)
	v_mov_b32_e32 v88, v8
	s_waitcnt lgkmcnt(2)
	v_mov_b32_e32 v89, v0
	v_and_b32_e32 v116, 0xffff0000, v20
	v_mov_b32_e32 v0, v9
	v_mov_b32_e32 v100, v10
	v_mov_b32_e32 v101, v2
	v_mov_b32_e32 v2, v11
	v_mov_b32_e32 v98, v12
	ds_read2_b64 v[8:11], v79 offset0:49 offset1:50
	s_waitcnt lgkmcnt(1)
	v_mov_b32_e32 v99, v58
	v_mov_b32_e32 v58, v13
	v_pk_fma_f32 v[12:13], v[88:89], v[114:115], 0 op_sel_hi:[1,0,0]
	v_lshlrev_b32_e32 v118, 16, v21
	v_pk_fma_f32 v[12:13], v[0:1], v[116:117], v[12:13] op_sel_hi:[1,0,1]
	ds_read2_b64 v[52:55], v79 offset0:48 offset1:51
	v_and_b32_e32 v120, 0xffff0000, v21
	v_pk_fma_f32 v[12:13], v[100:101], v[118:119], v[12:13] op_sel_hi:[1,0,1]
	v_lshlrev_b32_e32 v122, 16, v22
	v_pk_fma_f32 v[12:13], v[2:3], v[120:121], v[12:13] op_sel_hi:[1,0,1]
	v_and_b32_e32 v124, 0xffff0000, v22
	v_pk_fma_f32 v[12:13], v[98:99], v[122:123], v[12:13] op_sel_hi:[1,0,1]
	v_and_b32_e32 v127, 0xffff0000, v23
	v_lshlrev_b32_e32 v126, 16, v23
	v_mov_b32_e32 v96, v14
	v_mov_b32_e32 v97, v60
	v_pk_fma_f32 v[12:13], v[58:59], v[124:125], v[12:13] op_sel_hi:[1,0,1]
	v_mov_b32_e32 v60, v15
	v_pk_fma_f32 v[12:13], v[96:97], v[126:127], v[12:13] op_sel_hi:[1,0,1]
	v_mov_b32_e32 v80, v127
	s_waitcnt lgkmcnt(0)
	v_mov_b64_e32 v[94:95], v[54:55]
	ds_read_b128 v[54:57], v79 offset:512
	ds_read2_b64 v[4:7], v79 offset0:16 offset1:19
	v_pk_fma_f32 v[82:83], v[60:61], v[80:81], v[12:13] op_sel_hi:[1,0,1]
	ds_read_b128 v[66:69], v79 offset:768
	ds_read2_b64 v[12:15], v79 offset0:80 offset1:83
	ds_read_b128 v[62:65], v79 offset:528
	ds_read2_b64 v[16:19], v79 offset0:81 offset1:82
	ds_read_b128 v[70:73], v79 offset:784
	s_waitcnt lgkmcnt(6)
	v_mov_b32_e32 v102, v54
	s_waitcnt lgkmcnt(4)
	v_mov_b32_e32 v103, v66
	v_mov_b32_e32 v66, v55
	s_waitcnt lgkmcnt(2)
	v_mov_b32_e32 v106, v62
	s_waitcnt lgkmcnt(0)
; __device__ __forceinline__ float bf2f(short s) { return __uint_as_float(((unsigned)(unsigned short)s) << 16); }
; __device__ __forceinline__ void moba_unit(const Args& a, int l, LAS unsigned char* lds, int b, int h, int qb) {
;     ...
;         for (int qt = 0; qt < 2; ++qt) {
;             float g[8];
; #pragma unroll
;             for (int j = 0; j < 8; ++j) { float psum = 0.f;
;                 if (j < qb) {
; #pragma unroll
;                     for (int ks = 0; ks < 2; ++ks)
; #pragma unroll
;                         for (int i = 0; i < 8; ++i) psum += bf2f(qf[qt][ks][i]) * kml[j * 64 + ks * 32 + fq * 8 + i];
;                     psum += __shfl_xor(psum, 16); psum += __shfl_xor(psum, 32);
;                 }
;                 g[j] = (j < qb) ? psum : -INFINITY; }
	v_mov_b32_e32 v107, v70
	v_mov_b32_e32 v70, v63
	v_pk_fma_f32 v[62:63], v[102:103], v[114:115], 0 op_sel_hi:[1,0,0]
	v_mov_b32_e32 v104, v56
	v_mov_b32_e32 v105, v68
	v_pk_fma_f32 v[62:63], v[66:67], v[116:117], v[62:63] op_sel_hi:[1,0,1]
	v_mov_b32_e32 v68, v57
	v_pk_fma_f32 v[62:63], v[104:105], v[118:119], v[62:63] op_sel_hi:[1,0,1]
	v_mov_b32_e32 v108, v64
	v_pk_fma_f32 v[62:63], v[68:69], v[120:121], v[62:63] op_sel_hi:[1,0,1]
	v_mov_b32_e32 v109, v72
	v_mov_b32_e32 v72, v65
	v_pk_fma_f32 v[86:87], v[106:107], v[122:123], v[62:63] op_sel_hi:[1,0,1]
	ds_read2_b64 v[62:65], v79 offset0:112 offset1:115
	v_pk_fma_f32 v[86:87], v[70:71], v[124:125], v[86:87] op_sel_hi:[1,0,1]
	ds_read2_b64 v[54:57], v79 offset0:113 offset1:114
	v_pk_fma_f32 v[86:87], v[108:109], v[126:127], v[86:87] op_sel_hi:[1,0,1]
	s_waitcnt vmcnt(6)
	v_and_b32_e32 v111, 0xffff0000, v24
	v_lshlrev_b32_e32 v110, 16, v24
	v_mov_b32_e32 v84, v4
	v_mov_b32_e32 v85, v52
	v_pk_fma_f32 v[80:81], v[72:73], v[80:81], v[86:87] op_sel_hi:[1,0,1]
	v_mov_b32_e32 v86, v12
	s_waitcnt lgkmcnt(1)
	v_mov_b32_e32 v87, v62
	v_pk_fma_f32 v[82:83], v[84:85], v[110:111], v[82:83] op_sel_hi:[1,0,1]
	v_pk_fma_f32 v[80:81], v[86:87], v[110:111], v[80:81] op_sel_hi:[1,0,1]
	v_mov_b32_e32 v84, v13
	v_mov_b32_e32 v85, v63
	v_mov_b32_e32 v86, v111
	v_pk_fma_f32 v[80:81], v[84:85], v[86:87], v[80:81] op_sel_hi:[1,0,1]
	v_mov_b32_e32 v84, v5
	v_mov_b32_e32 v85, v53
	v_and_b32_e32 v113, 0xffff0000, v25
	v_lshlrev_b32_e32 v112, 16, v25
	v_pk_fma_f32 v[82:83], v[84:85], v[86:87], v[82:83] op_sel_hi:[1,0,1]
	v_mov_b32_e32 v84, v74
	v_mov_b32_e32 v85, v8
	v_pk_fma_f32 v[82:83], v[84:85], v[112:113], v[82:83] op_sel_hi:[1,0,1]
	v_mov_b32_e32 v84, v16
	s_waitcnt lgkmcnt(0)
	v_mov_b32_e32 v85, v54
	v_pk_fma_f32 v[80:81], v[84:85], v[112:113], v[80:81] op_sel_hi:[1,0,1]
	v_mov_b32_e32 v84, v17
	v_mov_b32_e32 v85, v55
	v_mov_b32_e32 v86, v113
	v_pk_fma_f32 v[80:81], v[84:85], v[86:87], v[80:81] op_sel_hi:[1,0,1]
	v_mov_b32_e32 v84, v75
	v_mov_b32_e32 v85, v9
	v_and_b32_e32 v91, 0xffff0000, v26
	v_lshlrev_b32_e32 v90, 16, v26
	v_pk_fma_f32 v[82:83], v[84:85], v[86:87], v[82:83] op_sel_hi:[1,0,1]
	v_mov_b32_e32 v84, v76
	v_mov_b32_e32 v85, v10
	v_pk_fma_f32 v[82:83], v[84:85], v[90:91], v[82:83] op_sel_hi:[1,0,1]
	v_mov_b32_e32 v84, v18
	v_mov_b32_e32 v85, v56
	v_pk_fma_f32 v[80:81], v[84:85], v[90:91], v[80:81] op_sel_hi:[1,0,1]
	v_mov_b32_e32 v84, v19
	v_mov_b32_e32 v85, v57
	v_mov_b32_e32 v86, v91
	v_pk_fma_f32 v[80:81], v[84:85], v[86:87], v[80:81] op_sel_hi:[1,0,1]
	v_mov_b32_e32 v84, v77
	v_mov_b32_e32 v85, v11
	v_and_b32_e32 v93, 0xffff0000, v27
	v_lshlrev_b32_e32 v92, 16, v27
	v_pk_fma_f32 v[82:83], v[84:85], v[86:87], v[82:83] op_sel_hi:[1,0,1]
	v_mov_b32_e32 v84, v6
	v_mov_b32_e32 v85, v94
	v_pk_fma_f32 v[82:83], v[84:85], v[92:93], v[82:83] op_sel_hi:[1,0,1]
	v_mov_b32_e32 v84, v14
	v_mov_b32_e32 v85, v64
	v_pk_fma_f32 v[80:81], v[84:85], v[92:93], v[80:81] op_sel_hi:[1,0,1]
	v_mov_b32_e32 v84, v15
	v_mov_b32_e32 v85, v65
	v_mov_b32_e32 v86, v93
	v_pk_fma_f32 v[80:81], v[84:85], v[86:87], v[80:81] op_sel_hi:[1,0,1]
	v_mov_b32_e32 v84, v7
	v_mov_b32_e32 v85, v95
	v_pk_fma_f32 v[82:83], v[84:85], v[86:87], v[82:83] op_sel_hi:[1,0,1]
	ds_bpermute_b32 v84, v198, v82
	ds_bpermute_b32 v86, v198, v80
	ds_bpermute_b32 v87, v198, v81
	ds_bpermute_b32 v85, v198, v83
	s_cmp_lg_u32 s19, 4
	s_cselect_b64 s[40:41], -1, 0
	v_mov_b32_e32 v117, 0xff800000
	s_waitcnt lgkmcnt(1)
	v_pk_add_f32 v[80:81], v[80:81], v[86:87]
	s_waitcnt lgkmcnt(0)
	v_pk_add_f32 v[82:83], v[82:83], v[84:85]
	ds_bpermute_b32 v84, v199, v82
	ds_bpermute_b32 v85, v199, v83
	ds_bpermute_b32 v86, v199, v80
	ds_bpermute_b32 v87, v199, v81
	s_and_b64 vcc, exec, s[40:41]
	v_mov_b32_e32 v119, 0xff800000
	s_cbranch_vccz .LBB0_551
	ds_read_b128 v[128:131], v79 offset:1024
	ds_read_b128 v[132:135], v79 offset:1040
	s_waitcnt lgkmcnt(1)
	v_fma_f32 v119, v128, v114, 0
	v_fmac_f32_e32 v119, v129, v116
	v_fmac_f32_e32 v119, v130, v118
	v_fmac_f32_e32 v119, v131, v120
	s_waitcnt lgkmcnt(0)
	v_fmac_f32_e32 v119, v132, v122
	v_fmac_f32_e32 v119, v133, v124
	v_pk_mul_f32 v[128:129], v[134:135], v[126:127]
	s_nop 0
	v_add_f32_e32 v119, v119, v128
	v_add_f32_e32 v119, v119, v129
	ds_read_b128 v[128:131], v79 offset:1152
	s_waitcnt lgkmcnt(0)
	v_pk_mul_f32 v[128:129], v[128:129], v[110:111]
	s_nop 0
	v_add_f32_e32 v119, v119, v128
	v_add_f32_e32 v119, v119, v129
	v_pk_mul_f32 v[128:129], v[130:131], v[112:113]
	s_nop 0
	v_add_f32_e32 v119, v119, v128
	v_add_f32_e32 v119, v119, v129
	ds_read_b128 v[128:131], v79 offset:1168
	s_waitcnt lgkmcnt(0)
	v_pk_mul_f32 v[128:129], v[128:129], v[90:91]
	s_nop 0
	v_add_f32_e32 v119, v119, v128
	v_add_f32_e32 v119, v119, v129
	v_pk_mul_f32 v[128:129], v[130:131], v[92:93]
	s_nop 0
	v_add_f32_e32 v119, v119, v128
	v_add_f32_e32 v119, v119, v129
	ds_bpermute_b32 v121, v198, v119
	s_waitcnt lgkmcnt(0)
	v_add_f32_e32 v119, v119, v121
	ds_bpermute_b32 v121, v199, v119
	s_waitcnt lgkmcnt(0)
	v_add_f32_e32 v119, v119, v121
